# GEMM: epilogue mode read once per phase into an SGPR instead of an LDS read per tile
# baseline (speedup 1.0000x reference)
.LBB0_796:
	s_add_i32 m0, s27, 0x18000
	v_lshl_add_u64 v[12:13], v[12:13], 0, s[92:93]
	s_waitcnt vmcnt(2)
	s_barrier
	global_load_lds_dwordx4 v[12:13], off
	v_lshl_add_u64 v[10:11], v[10:11], 0, s[92:93]
	s_add_i32 m0, s27, 0x1a000
	s_add_i32 s48, s27, 0x8000
	global_load_lds_dwordx4 v[10:11], off
	v_lshl_add_u64 v[6:7], v[6:7], 0, s[92:93]
	s_mov_b32 m0, s48
	s_add_i32 s49, s27, 0xa000
	global_load_lds_dwordx4 v[6:7], off
	v_lshl_add_u64 v[6:7], v[8:9], 0, s[92:93]
	s_mov_b32 m0, s49
	v_lshl_add_u64 v[4:5], v[4:5], 0, s[92:93]
	global_load_lds_dwordx4 v[6:7], off
	s_add_i32 m0, s27, 0x1c000
	v_lshl_add_u64 v[2:3], v[2:3], 0, s[92:93]
	global_load_lds_dwordx4 v[4:5], off
	s_add_i32 m0, s27, 0x1e000
	v_and_b32_e32 v202, 15, v0
	global_load_lds_dwordx4 v[2:3], off
	v_bfe_u32 v203, v0, 4, 2
	v_lshlrev_b32_e32 v2, 6, v202
	v_lshlrev_b32_e32 v0, 2, v0
	s_and_b32 s50, s7, 3
	v_lshl_or_b32 v2, v203, 4, v2
	s_lshl_b32 s0, s43, 13
	v_and_b32_e32 v0, 32, v0
	v_bitop3_b32 v3, v2, s0, v0 bitop3:0xde
	s_lshl_b32 s0, s50, 12
	s_cmpk_lt_u32 s6, 0x100
	s_cselect_b64 s[18:19], -1, 0
	s_ashr_i32 s11, s10, 31
	s_abs_i32 s55, s39
	v_bitop3_b32 v204, v2, s0, v0 bitop3:0xde
	s_lshr_b32 s0, s11, 29
	v_cvt_f32_u32_e32 v0, s55
	s_add_i32 s0, s10, s0
	s_ashr_i32 s52, s0, 3
	s_and_b32 s0, s0, -8
	s_lshl_b32 s56, s39, 3
	s_ashr_i32 s57, s39, 31
	s_sub_i32 s53, s10, s0
	s_add_i32 s0, s56, s57
	v_rcp_iflag_f32_e32 v0, v0
	s_xor_b32 s58, s0, s57
	v_cvt_f32_u32_e32 v2, s58
	s_sub_i32 s0, 0, s55
	v_mul_f32_e32 v0, 0x4f7ffffe, v0
	v_cvt_u32_f32_e32 v0, v0
	v_rcp_iflag_f32_e32 v2, v2
	s_waitcnt vmcnt(6)
	s_ashr_i32 s51, s38, 31
	v_readfirstlane_b32 s1, v0
	v_mul_f32_e32 v0, 0x4f7ffffe, v2
	v_cvt_u32_f32_e32 v0, v0
	s_mul_i32 s0, s0, s1
	s_mul_hi_u32 s0, s1, s0
	s_add_i32 s60, s1, s0
	s_sub_i32 s0, 0, s58
	v_readfirstlane_b32 s1, v0
	s_mul_i32 s0, s0, s1
	s_mul_hi_u32 s0, s1, s0
	s_add_i32 s54, s52, 1
	s_mov_b32 s59, 0
	s_add_i32 s61, s1, s0
	v_lshl_add_u64 v[156:157], s[12:13], 0, v[154:155]
	v_lshl_add_u64 v[158:159], s[12:13], 0, v[152:153]
	v_add_u32_e32 v205, 0, v3
	v_readlane_b32 s99, v253, 34
	s_nop 0
	v_mov_b32_e32 v0, s99
	ds_read_b32 v0, v0
	s_waitcnt lgkmcnt(0)
	v_readfirstlane_b32 s99, v0
	s_barrier
	s_branch .LBB0_799

.LBB0_814:
	v_mov_b32_e32 v163, v202
	v_mov_b32_e32 v147, v203
	s_mov_b32 s68, s43
	s_mov_b32 s30, s50
	s_lshl_b32 s31, s30, 5
	v_lshlrev_b32_e32 v148, 2, v147
	s_waitcnt lgkmcnt(0)
	s_mov_b32 s21, s99
	s_lshl_b32 s67, s66, 8
	v_lshl_add_u32 v206, s68, 6, v163
	s_lshl_b32 s4, s65, 8
	v_add_u32_e32 v146, s31, v148
	v_add_u32_e32 v160, s67, v206
	v_add_u32_e32 v162, s4, v146
	s_cmp_gt_u32 s21, 1
	s_mov_b64 s[2:3], -1
	s_cbranch_scc1 .LBB0_820
	s_and_b64 vcc, exec, s[2:3]
	s_cbranch_vccnz .LBB0_1037
